# attn3_stage
# speedup vs baseline: 1.0179x; 1.0026x over previous
; DEVI f32x4 mfma16(bf16x8 a, bf16x8 b, f32x4 c) { return __builtin_amdgcn_mfma_f32_16x16x32_bf16(a, b, c, 0, 0, 0); }
; DEVI void attn_phase(int wv, const Params& p, char* smem) {
;     ...
;     for (int kt = 0; kt < nkt; ++kt) {
;       const bool more = (kt + 1) < nkt;
;       if (more) {
;         u16* dK = sK + ((kt + 1) & 1) * 64 * 192;
;         u16* dV = sV + ((kt + 1) & 1) * 128 * 64;
;         ATT_STAGE(kt + 1, dK, dV);
;       }
;       const u16* cK = sK + (kt & 1) * 64 * 192;
;       const u16* cV = sV + (kt & 1) * 128 * 64;
;       f32x4 st[4][2];
; #pragma unroll
;       for (int i = 0; i < 4; ++i) { st[i][0] = zq; st[i][1] = zq; }
; #pragma unroll
;       for (int hh = 0; hh < 2; ++hh)
; #pragma unroll
;         for (int ks = 0; ks < 6; ++ks) {
;           const int sw = ((ks * 4 + g) ^ (fr & 7)) << 3;
; #pragma unroll
;           for (int mh = 0; mh < 2; ++mh) {
;             const int mt = hh * 2 + mh;
;             const bf16x8 kf = *(const bf16x8*)(cK + (mt * 16 + fr) * 192 + sw);
;             st[mt][0] = mfma16(kf, qf[0][ks], st[mt][0]);
;             st[mt][1] = mfma16(kf, qf[1][ks], st[mt][1]);
;           }
;         }
.Lattn_f_end:
	s_add_i32 s15, s15, 1
	s_add_i32 s19, s19, 64
	s_waitcnt vmcnt(0) lgkmcnt(0)
	s_barrier
	s_cmp_eq_u32 s18, s15
	s_cbranch_scc1 .LBB0_986
	v_sub_f32_e32 v184, 0, v181
	v_sub_f32_e32 v185, 0, v181
	v_sub_f32_e32 v186, 0, v181
	v_sub_f32_e32 v187, 0, v181
	v_sub_f32_e32 v188, 0, v180
	v_sub_f32_e32 v189, 0, v180
	v_sub_f32_e32 v190, 0, v180
	v_sub_f32_e32 v191, 0, v180
	v_mov_b32_e32 v253, 0x41000000
.Lattn_loop:
	s_add_i32 s5, s15, -1
	s_and_b32 s5, s5, 1
	s_and_b32 s22, s15, 1
	s_mul_i32 s21, s5, 0x6000
	s_mul_i32 s20, s22, 0x6000
	s_lshl_b32 s23, s5, 14
	s_lshl_b32 s4, s22, 14
	v_add_u32_e32 v210, s21, v202
	v_add_u32_e32 v211, s21, v203
	v_add_u32_e32 v212, s21, v204
	v_add_u32_e32 v213, s21, v205
	v_add_u32_e32 v214, s21, v206
	v_add_u32_e32 v215, s21, v207
	v_add_u32_e32 v216, s23, v208
	v_add_u32_e32 v217, s23, v209
	ds_read_b128 v[218:221], v210
	ds_read_b128 v[222:225], v210 offset:6144
	ds_read_b128 v[226:229], v211
	ds_read_b128 v[230:233], v211 offset:6144
	ds_read_b128 v[234:237], v212
	ds_read_b128 v[238:241], v212 offset:6144
	ds_read_b128 v[242:245], v213
	s_waitcnt lgkmcnt(6)
	v_mfma_f32_16x16x32_bf16 v[116:119], v[218:221], v[40:43], v[184:187]
	v_readfirstlane_b32 s5, v201
	v_mfma_f32_16x16x32_bf16 v[120:123], v[218:221], v[44:47], v[188:191]
	s_add_i32 s5, s5, s20
	ds_read_b128 v[246:249], v213 offset:6144
	s_waitcnt lgkmcnt(6)
	v_mfma_f32_16x16x32_bf16 v[124:127], v[222:225], v[40:43], v[184:187]
	s_mov_b32 m0, s5
	v_mfma_f32_16x16x32_bf16 v[128:131], v[222:225], v[44:47], v[188:191]
	s_nop 0
	ds_read_b128 v[218:221], v214
	s_waitcnt lgkmcnt(6)
	v_mfma_f32_16x16x32_bf16 v[116:119], v[226:229], v[32:35], v[116:119]
	global_load_lds_dwordx4 v193, s[0:1]
	v_mfma_f32_16x16x32_bf16 v[120:123], v[226:229], v[36:39], v[120:123]
	v_add_u32_e32 v193, v193, v196
	ds_read_b128 v[222:225], v214 offset:6144
	s_waitcnt lgkmcnt(6)
	v_mfma_f32_16x16x32_bf16 v[124:127], v[230:233], v[32:35], v[124:127]
	s_add_i32 s5, s5, 0x2000
	v_mfma_f32_16x16x32_bf16 v[128:131], v[230:233], v[36:39], v[128:131]
	s_mov_b32 m0, s5
	ds_read_b128 v[226:229], v215
	s_waitcnt lgkmcnt(6)
	v_mfma_f32_16x16x32_bf16 v[116:119], v[234:237], v[24:27], v[116:119]
	s_nop 0
	v_mfma_f32_16x16x32_bf16 v[120:123], v[234:237], v[28:31], v[120:123]
	global_load_lds_dwordx4 v194, s[0:1]
	ds_read_b128 v[230:233], v215 offset:6144
	s_waitcnt lgkmcnt(6)
	v_mfma_f32_16x16x32_bf16 v[124:127], v[238:241], v[24:27], v[124:127]
	v_add_u32_e32 v194, v194, v197
	v_mfma_f32_16x16x32_bf16 v[128:131], v[238:241], v[28:31], v[128:131]
	s_add_i32 s5, s5, 0x2000
	ds_read_b128 v[234:237], v210 offset:12288
	s_waitcnt lgkmcnt(6)
	v_mfma_f32_16x16x32_bf16 v[116:119], v[242:245], v[16:19], v[116:119]
	s_mov_b32 m0, s5
	v_mfma_f32_16x16x32_bf16 v[120:123], v[242:245], v[20:23], v[120:123]
	s_nop 0
	ds_read_b128 v[238:241], v210 offset:18432
	s_waitcnt lgkmcnt(6)
	v_mfma_f32_16x16x32_bf16 v[124:127], v[246:249], v[16:19], v[124:127]
	global_load_lds_dwordx4 v195, s[0:1]
	v_mfma_f32_16x16x32_bf16 v[128:131], v[246:249], v[20:23], v[128:131]
	v_add_u32_e32 v195, v195, v198
	ds_read_b128 v[242:245], v211 offset:12288
	s_waitcnt lgkmcnt(6)
	v_mfma_f32_16x16x32_bf16 v[116:119], v[218:221], v[8:11], v[116:119]
	v_mfma_f32_16x16x32_bf16 v[120:123], v[218:221], v[12:15], v[120:123]
	ds_read_b128 v[246:249], v211 offset:18432
	s_waitcnt lgkmcnt(6)
	v_mfma_f32_16x16x32_bf16 v[124:127], v[222:225], v[8:11], v[124:127]
	v_mfma_f32_16x16x32_bf16 v[128:131], v[222:225], v[12:15], v[128:131]
	ds_read_b128 v[218:221], v212 offset:12288
	s_waitcnt lgkmcnt(6)
	v_mfma_f32_16x16x32_bf16 v[116:119], v[226:229], v[0:3], v[116:119]
	v_mfma_f32_16x16x32_bf16 v[120:123], v[226:229], v[4:7], v[120:123]
	ds_read_b128 v[222:225], v212 offset:18432
	s_waitcnt lgkmcnt(6)
	v_mfma_f32_16x16x32_bf16 v[124:127], v[230:233], v[0:3], v[124:127]
	v_mfma_f32_16x16x32_bf16 v[128:131], v[230:233], v[4:7], v[128:131]
	ds_read_b128 v[226:229], v213 offset:12288
	s_waitcnt lgkmcnt(6)
	v_mfma_f32_16x16x32_bf16 v[132:135], v[234:237], v[40:43], v[184:187]
	v_readfirstlane_b32 s5, v201
	v_mfma_f32_16x16x32_bf16 v[136:139], v[234:237], v[44:47], v[188:191]
	s_add_i32 s5, s5, s4
	ds_read_b128 v[230:233], v213 offset:18432
	s_waitcnt lgkmcnt(6)
	v_mfma_f32_16x16x32_bf16 v[140:143], v[238:241], v[40:43], v[184:187]
	s_add_i32 s5, s5, 0xc000
	v_mfma_f32_16x16x32_bf16 v[144:147], v[238:241], v[44:47], v[188:191]
	s_mov_b32 m0, s5
	ds_read_b128 v[234:237], v214 offset:12288
	s_waitcnt lgkmcnt(6)
	v_mfma_f32_16x16x32_bf16 v[132:135], v[242:245], v[32:35], v[132:135]
	s_nop 0
	v_mfma_f32_16x16x32_bf16 v[136:139], v[242:245], v[36:39], v[136:139]
	global_load_lds_dwordx4 v199, s[2:3]
	ds_read_b128 v[238:241], v214 offset:18432
	s_waitcnt lgkmcnt(6)
	v_mfma_f32_16x16x32_bf16 v[140:143], v[246:249], v[32:35], v[140:143]
	v_add_u32_e32 v199, 0x80, v199
	v_mfma_f32_16x16x32_bf16 v[144:147], v[246:249], v[36:39], v[144:147]
	s_add_i32 s5, s5, 0x2000
	ds_read_b128 v[242:245], v215 offset:12288
	s_waitcnt lgkmcnt(6)
	v_mfma_f32_16x16x32_bf16 v[132:135], v[218:221], v[24:27], v[132:135]
	s_mov_b32 m0, s5
	v_mfma_f32_16x16x32_bf16 v[136:139], v[218:221], v[28:31], v[136:139]
	s_nop 0
	ds_read_b128 v[246:249], v215 offset:18432
	s_waitcnt lgkmcnt(6)
	v_mfma_f32_16x16x32_bf16 v[140:143], v[222:225], v[24:27], v[140:143]
	global_load_lds_dwordx4 v200, s[2:3]
	v_mfma_f32_16x16x32_bf16 v[144:147], v[222:225], v[28:31], v[144:147]
	v_add_u32_e32 v200, 0x80, v200
	ds_read_b128 v[218:221], v216
	s_waitcnt lgkmcnt(6)
; DEVI float sxor(float v, int mask, int lane) { return __int_as_float(__builtin_amdgcn_ds_bpermute((lane ^ mask) << 2, __float_as_int(v))); }
; DEVI f32x4 mfma16(bf16x8 a, bf16x8 b, f32x4 c) { return __builtin_amdgcn_mfma_f32_16x16x32_bf16(a, b, c, 0, 0, 0); }
; DEVI void attn_phase(int wv, const Params& p, char* smem) {
;     ...
; #pragma unroll
;       for (int kk = 0; kk < 2; ++kk) {
;         bf16x8 pf[2];
; #pragma unroll
;         for (int nt = 0; nt < 2; ++nt) {
;           float mx = st[2 * kk][nt][0];
; #pragma unroll
;           for (int mh = 0; mh < 2; ++mh)
; #pragma unroll
;             for (int j = 0; j < 4; ++j) mx = fmaxf(mx, st[2 * kk + mh][nt][j]);
;           if (__builtin_amdgcn_ballot_w64(mx > mrun[nt] + 8.f) != 0ull) {
;             mx = fmaxf(mx, sxor(mx, 16, lane));
;             mx = fmaxf(mx, sxor(mx, 32, lane));
;             const float mnew = mx > mrun[nt] + 8.f ? mx : mrun[nt];
;             const float alpha = __builtin_amdgcn_exp2f(mrun[nt] - mnew);
;             lrun[nt] *= alpha;
; #pragma unroll
;             for (int dt = 0; dt < 8; ++dt) ot[dt][nt] *= alpha;
;             mrun[nt] = mnew;
;           }
;           const float mref = mrun[nt];
;           float ps = 0.f;
; #pragma unroll
;           for (int mh = 0; mh < 2; ++mh)
; #pragma unroll
;             for (int j = 0; j < 4; ++j) {
;               const float pv = __builtin_amdgcn_exp2f(st[2 * kk + mh][nt][j] - mref);
;               ps += pv;
;               st[2 * kk + mh][nt][j] = pv;
;             }
;           lrun[nt] += ps;
;           u32x4 w;
;           w.x = pack2(st[2 * kk][nt][0], st[2 * kk][nt][1]);
;           w.y = pack2(st[2 * kk][nt][2], st[2 * kk][nt][3]);
;           w.z = pack2(st[2 * kk + 1][nt][0], st[2 * kk + 1][nt][1]);
;           w.w = pack2(st[2 * kk + 1][nt][2], st[2 * kk + 1][nt][3]);
;           pf[nt] = __builtin_bit_cast(bf16x8, w);
;         }
; #pragma unroll
;         for (int dt = 0; dt < 8; ++dt) {
;           const bf16x8 vf = *(const bf16x8*)(cV + (dt * 16 + fr) * 64 + (((kk * 4 + g) ^ (fr & 7)) << 3));
;           ot[dt][0] = mfma16(vf, pf[0], ot[dt][0]);
;           ot[dt][1] = mfma16(vf, pf[1], ot[dt][1]);
;         }
	v_mfma_f32_16x16x32_bf16 v[132:135], v[226:229], v[16:19], v[132:135]
	v_max3_f32 v250, v116, v117, v118
	v_mfma_f32_16x16x32_bf16 v[136:139], v[226:229], v[20:23], v[136:139]
	v_max3_f32 v251, v120, v121, v122
	ds_read_b128 v[222:225], v216 offset:2048
	s_waitcnt lgkmcnt(6)
	v_mfma_f32_16x16x32_bf16 v[140:143], v[230:233], v[16:19], v[140:143]
	v_max3_f32 v250, v250, v119, v124
	v_mfma_f32_16x16x32_bf16 v[144:147], v[230:233], v[20:23], v[144:147]
	v_max3_f32 v251, v251, v123, v128
	ds_read_b128 v[226:229], v216 offset:4096
	s_waitcnt lgkmcnt(6)
	v_mfma_f32_16x16x32_bf16 v[132:135], v[234:237], v[8:11], v[132:135]
	v_max3_f32 v250, v250, v125, v126
	v_mfma_f32_16x16x32_bf16 v[136:139], v[234:237], v[12:15], v[136:139]
	v_max3_f32 v251, v251, v129, v130
	ds_read_b128 v[230:233], v216 offset:6144
	s_waitcnt lgkmcnt(6)
	v_mfma_f32_16x16x32_bf16 v[140:143], v[238:241], v[8:11], v[140:143]
	v_max_f32_e32 v250, v250, v127
	v_mfma_f32_16x16x32_bf16 v[144:147], v[238:241], v[12:15], v[144:147]
	v_max_f32_e32 v251, v251, v131
	ds_read_b128 v[234:237], v216 offset:8192
	s_waitcnt lgkmcnt(6)
	v_mfma_f32_16x16x32_bf16 v[132:135], v[242:245], v[0:3], v[132:135]
	v_mfma_f32_16x16x32_bf16 v[136:139], v[242:245], v[4:7], v[136:139]
	ds_read_b128 v[238:241], v216 offset:10240
	s_waitcnt lgkmcnt(6)
	v_mfma_f32_16x16x32_bf16 v[140:143], v[246:249], v[0:3], v[140:143]
	v_mfma_f32_16x16x32_bf16 v[144:147], v[246:249], v[4:7], v[144:147]
	s_nop 2
	v_max3_f32 v250, v250, v132, v133
	v_max3_f32 v251, v251, v136, v137
	v_max3_f32 v250, v250, v134, v135
	v_max3_f32 v251, v251, v138, v139
	v_max3_f32 v250, v250, v140, v141
	v_max3_f32 v251, v251, v144, v145
	v_max3_f32 v250, v250, v142, v143
	v_max3_f32 v251, v251, v146, v147
	v_cmp_lt_f32_e32 vcc, 0x41000000, v250
	v_cmp_gt_f32_e64 s[22:23], v251, v253
	s_or_b64 s[22:23], vcc, s[22:23]
	s_cbranch_scc1 .Lattn3_resc
.Lattn3_resc_ret:
	v_exp_f32_e32 v116, v116
	v_exp_f32_e32 v120, v120
	v_exp_f32_e32 v117, v117
	v_exp_f32_e32 v121, v121
	v_exp_f32_e32 v118, v118
	v_exp_f32_e32 v122, v122
	v_exp_f32_e32 v119, v119
	v_exp_f32_e32 v123, v123
	v_exp_f32_e32 v124, v124
	v_exp_f32_e32 v128, v128
	v_exp_f32_e32 v125, v125
	v_exp_f32_e32 v129, v129
	v_exp_f32_e32 v126, v126
	v_exp_f32_e32 v130, v130
	v_exp_f32_e32 v127, v127
	v_exp_f32_e32 v131, v131
	v_add_f32_e32 v174, v116, v117
	v_add_f32_e32 v175, v120, v121
	v_add_f32_e32 v174, v174, v118
	v_add_f32_e32 v175, v175, v122
	v_add_f32_e32 v174, v174, v119
	v_add_f32_e32 v175, v175, v123
	v_add_f32_e32 v174, v174, v124
	v_add_f32_e32 v175, v175, v128
	v_add_f32_e32 v174, v174, v125
	v_add_f32_e32 v175, v175, v129
	v_add_f32_e32 v174, v174, v126
	v_add_f32_e32 v175, v175, v130
	v_add_f32_e32 v174, v174, v127
	v_add_f32_e32 v175, v175, v131
	v_add_f32_e32 v183, v183, v174
	v_add_f32_e32 v182, v182, v175
	v_cvt_pk_bf16_f32 v116, v116, v117
	v_cvt_pk_bf16_f32 v120, v120, v121
	v_cvt_pk_bf16_f32 v117, v118, v119
	v_cvt_pk_bf16_f32 v121, v122, v123
	v_cvt_pk_bf16_f32 v118, v124, v125
	v_cvt_pk_bf16_f32 v122, v128, v129
	v_cvt_pk_bf16_f32 v119, v126, v127
	v_cvt_pk_bf16_f32 v123, v130, v131
	ds_read_b128 v[242:245], v216 offset:12288
	s_waitcnt lgkmcnt(6)
	v_mfma_f32_16x16x32_bf16 v[112:115], v[218:221], v[116:119], v[112:115]
	v_exp_f32_e32 v132, v132
	v_exp_f32_e32 v136, v136
	v_exp_f32_e32 v133, v133
	v_mfma_f32_16x16x32_bf16 v[108:111], v[218:221], v[120:123], v[108:111]
	v_exp_f32_e32 v137, v137
	v_exp_f32_e32 v134, v134
	v_exp_f32_e32 v138, v138
	ds_read_b128 v[246:249], v216 offset:14336
	s_waitcnt lgkmcnt(6)
	v_mfma_f32_16x16x32_bf16 v[104:107], v[222:225], v[116:119], v[104:107]
	v_exp_f32_e32 v135, v135
	v_exp_f32_e32 v139, v139
	v_exp_f32_e32 v140, v140
	v_mfma_f32_16x16x32_bf16 v[100:103], v[222:225], v[120:123], v[100:103]
	v_exp_f32_e32 v144, v144
	v_exp_f32_e32 v141, v141
	v_exp_f32_e32 v145, v145
	ds_read_b128 v[218:221], v217
	s_waitcnt lgkmcnt(6)
	v_mfma_f32_16x16x32_bf16 v[96:99], v[226:229], v[116:119], v[96:99]
	v_exp_f32_e32 v142, v142
	v_exp_f32_e32 v146, v146
	v_exp_f32_e32 v143, v143
	v_mfma_f32_16x16x32_bf16 v[92:95], v[226:229], v[120:123], v[92:95]
	v_exp_f32_e32 v147, v147
	v_add_f32_e32 v174, v132, v133
	v_add_f32_e32 v175, v136, v137
	ds_read_b128 v[222:225], v217 offset:2048
	s_waitcnt lgkmcnt(6)
	v_mfma_f32_16x16x32_bf16 v[88:91], v[230:233], v[116:119], v[88:91]
	v_add_f32_e32 v174, v174, v134
	v_add_f32_e32 v175, v175, v138
	v_add_f32_e32 v174, v174, v135
	v_mfma_f32_16x16x32_bf16 v[84:87], v[230:233], v[120:123], v[84:87]
	v_add_f32_e32 v175, v175, v139
	v_add_f32_e32 v174, v174, v140
	v_add_f32_e32 v175, v175, v144
	ds_read_b128 v[226:229], v217 offset:4096
	s_waitcnt lgkmcnt(6)
	v_mfma_f32_16x16x32_bf16 v[76:79], v[234:237], v[116:119], v[76:79]
	v_add_f32_e32 v174, v174, v141
	v_add_f32_e32 v175, v175, v145
	v_add_f32_e32 v174, v174, v142
	v_mfma_f32_16x16x32_bf16 v[68:71], v[234:237], v[120:123], v[68:71]
	v_add_f32_e32 v175, v175, v146
	v_add_f32_e32 v174, v174, v143
	v_add_f32_e32 v175, v175, v147
	ds_read_b128 v[230:233], v217 offset:6144
	s_waitcnt lgkmcnt(6)
	v_mfma_f32_16x16x32_bf16 v[60:63], v[238:241], v[116:119], v[60:63]
	v_add_f32_e32 v183, v183, v174
	v_add_f32_e32 v182, v182, v175
	v_cvt_pk_bf16_f32 v132, v132, v133
	v_mfma_f32_16x16x32_bf16 v[56:59], v[238:241], v[120:123], v[56:59]
	v_cvt_pk_bf16_f32 v136, v136, v137
	v_cvt_pk_bf16_f32 v133, v134, v135
	v_cvt_pk_bf16_f32 v137, v138, v139
	ds_read_b128 v[234:237], v217 offset:8192
	s_waitcnt lgkmcnt(6)
; DEVI float sxor(float v, int mask, int lane) { return __int_as_float(__builtin_amdgcn_ds_bpermute((lane ^ mask) << 2, __float_as_int(v))); }
; DEVI f32x4 mfma16(bf16x8 a, bf16x8 b, f32x4 c) { return __builtin_amdgcn_mfma_f32_16x16x32_bf16(a, b, c, 0, 0, 0); }
; DEVI void attn_phase(int wv, const Params& p, char* smem) {
;     ...
;           if (__builtin_amdgcn_ballot_w64(mx > mrun[nt] + 8.f) != 0ull) {
;             mx = fmaxf(mx, sxor(mx, 16, lane));
;             mx = fmaxf(mx, sxor(mx, 32, lane));
;             const float mnew = mx > mrun[nt] + 8.f ? mx : mrun[nt];
;             const float alpha = __builtin_amdgcn_exp2f(mrun[nt] - mnew);
;             lrun[nt] *= alpha;
; #pragma unroll
;             for (int dt = 0; dt < 8; ++dt) ot[dt][nt] *= alpha;
;             mrun[nt] = mnew;
;           }
;     ...
; #pragma unroll
;         for (int dt = 0; dt < 8; ++dt) {
;           const bf16x8 vf = *(const bf16x8*)(cV + (dt * 16 + fr) * 64 + (((kk * 4 + g) ^ (fr & 7)) << 3));
;           ot[dt][0] = mfma16(vf, pf[0], ot[dt][0]);
;           ot[dt][1] = mfma16(vf, pf[1], ot[dt][1]);
;         }
;       }
;       asm volatile("s_waitcnt vmcnt(0)" ::: "memory");
;       __syncthreads();
;     }
	v_mfma_f32_16x16x32_bf16 v[80:83], v[242:245], v[116:119], v[80:83]
	v_cvt_pk_bf16_f32 v134, v140, v141
	v_cvt_pk_bf16_f32 v138, v144, v145
	v_cvt_pk_bf16_f32 v135, v142, v143
	v_mfma_f32_16x16x32_bf16 v[72:75], v[242:245], v[120:123], v[72:75]
	v_cvt_pk_bf16_f32 v139, v146, v147
	ds_read_b128 v[238:241], v217 offset:10240
	s_waitcnt lgkmcnt(6)
	v_mfma_f32_16x16x32_bf16 v[64:67], v[246:249], v[116:119], v[64:67]
	v_mfma_f32_16x16x32_bf16 v[52:55], v[246:249], v[120:123], v[52:55]
	ds_read_b128 v[242:245], v217 offset:12288
	s_waitcnt lgkmcnt(6)
	v_mfma_f32_16x16x32_bf16 v[112:115], v[218:221], v[132:135], v[112:115]
	v_mfma_f32_16x16x32_bf16 v[108:111], v[218:221], v[136:139], v[108:111]
	ds_read_b128 v[246:249], v217 offset:14336
	s_waitcnt lgkmcnt(6)
	v_mfma_f32_16x16x32_bf16 v[104:107], v[222:225], v[132:135], v[104:107]
	v_mfma_f32_16x16x32_bf16 v[100:103], v[222:225], v[136:139], v[100:103]
	s_waitcnt lgkmcnt(5)
	v_mfma_f32_16x16x32_bf16 v[96:99], v[226:229], v[132:135], v[96:99]
	v_mfma_f32_16x16x32_bf16 v[92:95], v[226:229], v[136:139], v[92:95]
	s_waitcnt lgkmcnt(4)
	v_mfma_f32_16x16x32_bf16 v[88:91], v[230:233], v[132:135], v[88:91]
	v_mfma_f32_16x16x32_bf16 v[84:87], v[230:233], v[136:139], v[84:87]
	s_waitcnt lgkmcnt(3)
	v_mfma_f32_16x16x32_bf16 v[76:79], v[234:237], v[132:135], v[76:79]
	v_mfma_f32_16x16x32_bf16 v[68:71], v[234:237], v[136:139], v[68:71]
	s_waitcnt lgkmcnt(2)
	v_mfma_f32_16x16x32_bf16 v[60:63], v[238:241], v[132:135], v[60:63]
	v_mfma_f32_16x16x32_bf16 v[56:59], v[238:241], v[136:139], v[56:59]
	s_waitcnt lgkmcnt(1)
	v_mfma_f32_16x16x32_bf16 v[80:83], v[242:245], v[132:135], v[80:83]
	v_mfma_f32_16x16x32_bf16 v[72:75], v[242:245], v[136:139], v[72:75]
	s_waitcnt lgkmcnt(0)
	v_mfma_f32_16x16x32_bf16 v[64:67], v[246:249], v[132:135], v[64:67]
	v_mfma_f32_16x16x32_bf16 v[52:55], v[246:249], v[136:139], v[52:55]
	s_add_i32 s15, s15, 1
	s_waitcnt vmcnt(0) lgkmcnt(0)
	s_barrier
	s_cmp_eq_u32 s18, s15
	s_cbranch_scc0 .Lattn_loop
	s_branch .LBB0_986
.Lattn3_resc:
	s_nop 7
	ds_bpermute_b32 v174, v161, v250
	s_waitcnt lgkmcnt(0)
	v_max_f32_e32 v250, v250, v174
	ds_bpermute_b32 v174, v162, v250
	s_waitcnt lgkmcnt(0)
	v_max_f32_e32 v250, v250, v174
	v_cmp_lt_f32_e32 vcc, 0x41000000, v250
	s_nop 1
	v_cndmask_b32_e32 v250, 0, v250, vcc
	v_sub_f32_e32 v174, 0, v250
	v_exp_f32_e32 v174, v174
	v_add_f32_e32 v181, v181, v250
	v_sub_f32_e32 v184, v184, v250
	v_sub_f32_e32 v185, v185, v250
	v_sub_f32_e32 v186, v186, v250
	v_sub_f32_e32 v187, v187, v250
	v_mul_f32_e32 v183, v183, v174
	v_pk_mul_f32 v[112:113], v[112:113], v[174:175] op_sel_hi:[1,0]
	v_pk_mul_f32 v[114:115], v[114:115], v[174:175] op_sel_hi:[1,0]
	v_pk_mul_f32 v[104:105], v[104:105], v[174:175] op_sel_hi:[1,0]
	v_pk_mul_f32 v[106:107], v[106:107], v[174:175] op_sel_hi:[1,0]
	v_pk_mul_f32 v[96:97], v[96:97], v[174:175] op_sel_hi:[1,0]
	v_pk_mul_f32 v[98:99], v[98:99], v[174:175] op_sel_hi:[1,0]
	v_pk_mul_f32 v[88:89], v[88:89], v[174:175] op_sel_hi:[1,0]
	v_pk_mul_f32 v[90:91], v[90:91], v[174:175] op_sel_hi:[1,0]
	v_pk_mul_f32 v[76:77], v[76:77], v[174:175] op_sel_hi:[1,0]
	v_pk_mul_f32 v[78:79], v[78:79], v[174:175] op_sel_hi:[1,0]
	v_pk_mul_f32 v[60:61], v[60:61], v[174:175] op_sel_hi:[1,0]
	v_pk_mul_f32 v[62:63], v[62:63], v[174:175] op_sel_hi:[1,0]
	v_pk_mul_f32 v[80:81], v[80:81], v[174:175] op_sel_hi:[1,0]
	v_pk_mul_f32 v[82:83], v[82:83], v[174:175] op_sel_hi:[1,0]
	v_pk_mul_f32 v[64:65], v[64:65], v[174:175] op_sel_hi:[1,0]
	v_pk_mul_f32 v[66:67], v[66:67], v[174:175] op_sel_hi:[1,0]
	v_sub_f32_e32 v116, v116, v250
	v_sub_f32_e32 v117, v117, v250
	v_sub_f32_e32 v118, v118, v250
	v_sub_f32_e32 v119, v119, v250
	v_sub_f32_e32 v124, v124, v250
	v_sub_f32_e32 v125, v125, v250
	v_sub_f32_e32 v126, v126, v250
	v_sub_f32_e32 v127, v127, v250
	v_sub_f32_e32 v132, v132, v250
	v_sub_f32_e32 v133, v133, v250
	v_sub_f32_e32 v134, v134, v250
	v_sub_f32_e32 v135, v135, v250
	v_sub_f32_e32 v140, v140, v250
	v_sub_f32_e32 v141, v141, v250
	v_sub_f32_e32 v142, v142, v250
	v_sub_f32_e32 v143, v143, v250
	ds_bpermute_b32 v252, v161, v251
	s_waitcnt lgkmcnt(0)
	v_max_f32_e32 v251, v251, v252
	ds_bpermute_b32 v252, v162, v251
	s_waitcnt lgkmcnt(0)
	v_max_f32_e32 v251, v251, v252
	v_cmp_lt_f32_e32 vcc, 0x41000000, v251
	s_nop 1
	v_cndmask_b32_e32 v251, 0, v251, vcc
	v_sub_f32_e32 v252, 0, v251
	v_exp_f32_e32 v252, v252
	v_add_f32_e32 v180, v180, v251
	v_sub_f32_e32 v188, v188, v251
	v_sub_f32_e32 v189, v189, v251
	v_sub_f32_e32 v190, v190, v251
	v_sub_f32_e32 v191, v191, v251
	v_mul_f32_e32 v182, v182, v252
	v_pk_mul_f32 v[108:109], v[108:109], v[252:253] op_sel_hi:[1,0]
	v_pk_mul_f32 v[110:111], v[110:111], v[252:253] op_sel_hi:[1,0]
	v_pk_mul_f32 v[100:101], v[100:101], v[252:253] op_sel_hi:[1,0]
	v_pk_mul_f32 v[102:103], v[102:103], v[252:253] op_sel_hi:[1,0]
	v_pk_mul_f32 v[92:93], v[92:93], v[252:253] op_sel_hi:[1,0]
	v_pk_mul_f32 v[94:95], v[94:95], v[252:253] op_sel_hi:[1,0]
	v_pk_mul_f32 v[84:85], v[84:85], v[252:253] op_sel_hi:[1,0]
	v_pk_mul_f32 v[86:87], v[86:87], v[252:253] op_sel_hi:[1,0]
	v_pk_mul_f32 v[68:69], v[68:69], v[252:253] op_sel_hi:[1,0]
	v_pk_mul_f32 v[70:71], v[70:71], v[252:253] op_sel_hi:[1,0]
	v_pk_mul_f32 v[56:57], v[56:57], v[252:253] op_sel_hi:[1,0]
	v_pk_mul_f32 v[58:59], v[58:59], v[252:253] op_sel_hi:[1,0]
	v_pk_mul_f32 v[72:73], v[72:73], v[252:253] op_sel_hi:[1,0]
	v_pk_mul_f32 v[74:75], v[74:75], v[252:253] op_sel_hi:[1,0]
	v_pk_mul_f32 v[52:53], v[52:53], v[252:253] op_sel_hi:[1,0]
	v_pk_mul_f32 v[54:55], v[54:55], v[252:253] op_sel_hi:[1,0]
	v_sub_f32_e32 v120, v120, v251
	v_sub_f32_e32 v121, v121, v251
	v_sub_f32_e32 v122, v122, v251
	v_sub_f32_e32 v123, v123, v251
	v_sub_f32_e32 v128, v128, v251
	v_sub_f32_e32 v129, v129, v251
	v_sub_f32_e32 v130, v130, v251
	v_sub_f32_e32 v131, v131, v251
	v_sub_f32_e32 v136, v136, v251
	v_sub_f32_e32 v137, v137, v251
	v_sub_f32_e32 v138, v138, v251
	v_sub_f32_e32 v139, v139, v251
	v_sub_f32_e32 v144, v144, v251
	v_sub_f32_e32 v145, v145, v251
	v_sub_f32_e32 v146, v146, v251
	v_sub_f32_e32 v147, v147, v251
	s_nop 1
	s_branch .Lattn3_resc_ret
